# loop-edge edits in the diff-attention tile loops: diagonal mask, rescale and drain-wait blocks moved out of line, common path falls through (one taken branch per tile instead of four)
# baseline (speedup 1.0000x reference)
.Lmy_a_nok2:
	s_waitcnt lgkmcnt(2)
	v_mfma_f32_32x32x16_bf16 v[130:145], v[248:251], v[166:169], v[130:145]
	s_waitcnt lgkmcnt(1)
	v_mfma_f32_32x32x16_bf16 v[130:145], v[214:217], v[170:173], v[130:145]
	s_waitcnt lgkmcnt(0)
	v_mfma_f32_32x32x16_bf16 v[130:145], v[188:191], v[174:177], v[130:145]
	s_lshl_b32 s3, s49, 14
	v_add_u32_e32 v252, s3, v224
	v_add_u32_e32 v253, s3, v228
	ds_read_b64_tr_b16 v[190:191], v252 offset:49152
	ds_read_b64_tr_b16 v[192:193], v252 offset:53248
	ds_read_b64_tr_b16 v[248:249], v253 offset:49152
	ds_read_b64_tr_b16 v[250:251], v253 offset:53248
	s_cmp_lt_u32 s0, s43
	s_cbranch_scc0 .Lmy_a_mask

.Lmy_a_nov2:
	s_waitcnt lgkmcnt(4)
	v_mfma_f32_32x32x16_bf16 v[82:97], v[178:181], v[182:185], v[82:97]
	ds_read_b64_tr_b16 v[182:183], v253 offset:57600
	ds_read_b64_tr_b16 v[184:185], v253 offset:61696
	v_sub_f32_e32 v140, v140, v0
	v_exp_f32_e32 v140, v140
	v_add_f32_e32 v130, v139, v130
	s_waitcnt lgkmcnt(4)
	v_mfma_f32_32x32x16_bf16 v[66:81], v[178:181], v[248:251], v[66:81]
	ds_read_b64_tr_b16 v[248:249], v254 offset:57600
	ds_read_b64_tr_b16 v[250:251], v254 offset:61696
	v_sub_f32_e32 v141, v141, v0
	v_exp_f32_e32 v141, v141
	v_add_f32_e32 v130, v140, v130
	s_waitcnt lgkmcnt(4)
	v_mfma_f32_32x32x16_bf16 v[50:65], v[178:181], v[190:193], v[50:65]
	ds_read_b64_tr_b16 v[190:191], v195 offset:57600
	ds_read_b64_tr_b16 v[192:193], v195 offset:61696
	v_sub_f32_e32 v142, v142, v0
	v_exp_f32_e32 v142, v142
	v_add_f32_e32 v130, v141, v130
	s_waitcnt lgkmcnt(4)
	v_mfma_f32_32x32x16_bf16 v[34:49], v[178:181], v[182:185], v[34:49]
	v_sub_f32_e32 v143, v143, v0
	v_exp_f32_e32 v143, v143
	v_add_f32_e32 v130, v142, v130
	s_waitcnt lgkmcnt(2)
	v_mfma_f32_32x32x16_bf16 v[18:33], v[178:181], v[248:251], v[18:33]
	v_sub_f32_e32 v144, v144, v0
	v_exp_f32_e32 v144, v144
	v_add_f32_e32 v130, v143, v130
	s_waitcnt lgkmcnt(0)
	v_mfma_f32_32x32x16_bf16 v[2:17], v[178:181], v[190:193], v[2:17]
	v_sub_f32_e32 v145, v145, v0
	v_exp_f32_e32 v145, v145
	v_add_f32_e32 v130, v144, v130
	s_cbranch_vccnz .Lmy_a_resc

.Lmy_a_mask:
	v_add_u32_e32 v0, s46, v223
	v_add_u32_e32 v187, 32, v0
	v_cmp_lt_u32_e32 vcc, v187, v201
	s_nop 1
	v_cndmask_b32_e32 v131, v246, v131, vcc
	v_cmp_le_u32_e32 vcc, v187, v201
	v_add_u32_e32 v187, 34, v0
	s_nop 0
	v_cndmask_b32_e32 v130, v246, v130, vcc
	v_cmp_le_u32_e32 vcc, v187, v201
	v_add_u32_e32 v187, 35, v0
	s_nop 0
	v_cndmask_b32_e32 v132, v246, v132, vcc
	v_cmp_le_u32_e32 vcc, v187, v201
	v_add_u32_e32 v187, 40, v0
	s_nop 0
	v_cndmask_b32_e32 v133, v246, v133, vcc
	v_cmp_le_u32_e32 vcc, v187, v201
	v_add_u32_e32 v187, 41, v0
	s_nop 0
	v_cndmask_b32_e32 v134, v246, v134, vcc
	v_cmp_le_u32_e32 vcc, v187, v201
	v_add_u32_e32 v187, 42, v0
	s_nop 0
	v_cndmask_b32_e32 v135, v246, v135, vcc
	v_cmp_le_u32_e32 vcc, v187, v201
	v_add_u32_e32 v187, 43, v0
	s_nop 0
	v_cndmask_b32_e32 v136, v246, v136, vcc
	v_cmp_le_u32_e32 vcc, v187, v201
	v_add_u32_e32 v187, 48, v0
	s_nop 0
	v_cndmask_b32_e32 v137, v246, v137, vcc
	v_cmp_le_u32_e32 vcc, v187, v201
	v_add_u32_e32 v187, 49, v0
	s_nop 0
	v_cndmask_b32_e32 v138, v246, v138, vcc
	v_cmp_le_u32_e32 vcc, v187, v201
	v_add_u32_e32 v187, 50, v0
	s_nop 0
	v_cndmask_b32_e32 v139, v246, v139, vcc
	v_cmp_le_u32_e32 vcc, v187, v201
	v_add_u32_e32 v187, 51, v0
	s_nop 0
	v_cndmask_b32_e32 v140, v246, v140, vcc
	v_cmp_le_u32_e32 vcc, v187, v201
	v_add_u32_e32 v187, 56, v0
	s_nop 0
	v_cndmask_b32_e32 v141, v246, v141, vcc
	v_cmp_le_u32_e32 vcc, v187, v201
	v_add_u32_e32 v187, 57, v0
	s_nop 0
	v_cndmask_b32_e32 v142, v246, v142, vcc
	v_cmp_le_u32_e32 vcc, v187, v201
	v_add_u32_e32 v187, 58, v0
	v_add_u32_e32 v0, 59, v0
	v_cndmask_b32_e32 v143, v246, v143, vcc
	v_cmp_le_u32_e32 vcc, v187, v201
	s_nop 1
	v_cndmask_b32_e32 v144, v246, v144, vcc
	v_cmp_le_u32_e32 vcc, v0, v201
	s_nop 1
	v_cndmask_b32_e32 v145, v246, v145, vcc
	s_branch .LBB0_293
.Lmy_a_resc:
	ds_write_b32 v226, v247
	ds_read_b128 v[190:193], v227 offset:96
	ds_read_b128 v[186:189], v227 offset:64
	ds_read_b128 v[182:185], v227 offset:32
	ds_read_b128 v[178:181], v227
	s_waitcnt lgkmcnt(3)
	v_pk_mul_f32 v[128:129], v[128:129], v[192:193]
	s_waitcnt lgkmcnt(2)
	v_pk_mul_f32 v[124:125], v[124:125], v[188:189]
	s_waitcnt lgkmcnt(1)
	v_pk_mul_f32 v[120:121], v[120:121], v[184:185]
	s_waitcnt lgkmcnt(0)
	v_pk_mul_f32 v[116:117], v[116:117], v[180:181]
	v_pk_mul_f32 v[126:127], v[126:127], v[190:191]
	v_pk_mul_f32 v[122:123], v[122:123], v[186:187]
	v_pk_mul_f32 v[118:119], v[118:119], v[182:183]
	v_pk_mul_f32 v[114:115], v[114:115], v[178:179]
	v_pk_mul_f32 v[112:113], v[112:113], v[192:193]
	v_pk_mul_f32 v[108:109], v[108:109], v[188:189]
	v_pk_mul_f32 v[104:105], v[104:105], v[184:185]
	v_pk_mul_f32 v[100:101], v[100:101], v[180:181]
	v_pk_mul_f32 v[110:111], v[110:111], v[190:191]
	v_pk_mul_f32 v[106:107], v[106:107], v[186:187]
	v_pk_mul_f32 v[102:103], v[102:103], v[182:183]
	v_pk_mul_f32 v[98:99], v[98:99], v[178:179]
	v_pk_mul_f32 v[96:97], v[96:97], v[192:193]
	v_pk_mul_f32 v[92:93], v[92:93], v[188:189]
	v_pk_mul_f32 v[88:89], v[88:89], v[184:185]
	v_pk_mul_f32 v[84:85], v[84:85], v[180:181]
	v_pk_mul_f32 v[94:95], v[94:95], v[190:191]
	v_pk_mul_f32 v[90:91], v[90:91], v[186:187]
	v_pk_mul_f32 v[86:87], v[86:87], v[182:183]
	v_pk_mul_f32 v[82:83], v[82:83], v[178:179]
	v_pk_mul_f32 v[80:81], v[80:81], v[192:193]
	v_pk_mul_f32 v[76:77], v[76:77], v[188:189]
	v_pk_mul_f32 v[72:73], v[72:73], v[184:185]
	v_pk_mul_f32 v[68:69], v[68:69], v[180:181]
	v_pk_mul_f32 v[78:79], v[78:79], v[190:191]
	v_pk_mul_f32 v[74:75], v[74:75], v[186:187]
	v_pk_mul_f32 v[70:71], v[70:71], v[182:183]
	v_pk_mul_f32 v[66:67], v[66:67], v[178:179]
	v_pk_mul_f32 v[64:65], v[64:65], v[192:193]
	v_pk_mul_f32 v[60:61], v[60:61], v[188:189]
	v_pk_mul_f32 v[56:57], v[56:57], v[184:185]
	v_pk_mul_f32 v[52:53], v[52:53], v[180:181]
	v_pk_mul_f32 v[62:63], v[62:63], v[190:191]
	v_pk_mul_f32 v[58:59], v[58:59], v[186:187]
	v_pk_mul_f32 v[54:55], v[54:55], v[182:183]
	v_pk_mul_f32 v[50:51], v[50:51], v[178:179]
	v_pk_mul_f32 v[48:49], v[48:49], v[192:193]
	v_pk_mul_f32 v[44:45], v[44:45], v[188:189]
	v_pk_mul_f32 v[40:41], v[40:41], v[184:185]
	v_pk_mul_f32 v[36:37], v[36:37], v[180:181]
	v_pk_mul_f32 v[46:47], v[46:47], v[190:191]
	v_pk_mul_f32 v[42:43], v[42:43], v[186:187]
	v_pk_mul_f32 v[38:39], v[38:39], v[182:183]
	v_pk_mul_f32 v[34:35], v[34:35], v[178:179]
	v_pk_mul_f32 v[32:33], v[32:33], v[192:193]
	v_pk_mul_f32 v[28:29], v[28:29], v[188:189]
	v_pk_mul_f32 v[24:25], v[24:25], v[184:185]
	v_pk_mul_f32 v[20:21], v[20:21], v[180:181]
	v_pk_mul_f32 v[30:31], v[30:31], v[190:191]
	v_pk_mul_f32 v[26:27], v[26:27], v[186:187]
	v_pk_mul_f32 v[22:23], v[22:23], v[182:183]
	v_pk_mul_f32 v[18:19], v[18:19], v[178:179]
	v_pk_mul_f32 v[16:17], v[16:17], v[192:193]
	v_pk_mul_f32 v[12:13], v[12:13], v[188:189]
	v_pk_mul_f32 v[8:9], v[8:9], v[184:185]
	v_pk_mul_f32 v[4:5], v[4:5], v[180:181]
	v_pk_mul_f32 v[14:15], v[14:15], v[190:191]
	v_pk_mul_f32 v[10:11], v[10:11], v[186:187]
	v_pk_mul_f32 v[6:7], v[6:7], v[182:183]
	v_pk_mul_f32 v[2:3], v[2:3], v[178:179]
	s_branch .LBB0_295
.Lmy_a_drain:
	s_waitcnt vmcnt(0)
	s_barrier
	s_branch .Lmy_a_go

.Lmy_b_nok2:
	s_waitcnt lgkmcnt(2)
	v_mfma_f32_32x32x16_bf16 v[130:145], v[248:251], v[166:169], v[130:145]
	s_waitcnt lgkmcnt(1)
	v_mfma_f32_32x32x16_bf16 v[130:145], v[214:217], v[170:173], v[130:145]
	s_waitcnt lgkmcnt(0)
	v_mfma_f32_32x32x16_bf16 v[130:145], v[188:191], v[174:177], v[130:145]
	s_lshl_b32 s3, s47, 14
	v_add_u32_e32 v252, s3, v224
	v_add_u32_e32 v253, s3, v228
	ds_read_b64_tr_b16 v[190:191], v252 offset:49152
	ds_read_b64_tr_b16 v[192:193], v252 offset:53248
	ds_read_b64_tr_b16 v[248:249], v253 offset:49152
	ds_read_b64_tr_b16 v[250:251], v253 offset:53248
	s_cmp_lt_u32 s0, s41
	s_cbranch_scc0 .Lmy_b_mask

.Lmy_b_mask:
	v_add_u32_e32 v0, s44, v223
	v_add_u32_e32 v187, 32, v0
	v_cmp_lt_u32_e32 vcc, v187, v201
	s_nop 1
	v_cndmask_b32_e32 v131, v246, v131, vcc
	v_cmp_le_u32_e32 vcc, v187, v201
	v_add_u32_e32 v187, 34, v0
	s_nop 0
	v_cndmask_b32_e32 v130, v246, v130, vcc
	v_cmp_le_u32_e32 vcc, v187, v201
	v_add_u32_e32 v187, 35, v0
	s_nop 0
	v_cndmask_b32_e32 v132, v246, v132, vcc
	v_cmp_le_u32_e32 vcc, v187, v201
	v_add_u32_e32 v187, 40, v0
	s_nop 0
	v_cndmask_b32_e32 v133, v246, v133, vcc
	v_cmp_le_u32_e32 vcc, v187, v201
	v_add_u32_e32 v187, 41, v0
	s_nop 0
	v_cndmask_b32_e32 v134, v246, v134, vcc
	v_cmp_le_u32_e32 vcc, v187, v201
	v_add_u32_e32 v187, 42, v0
	s_nop 0
	v_cndmask_b32_e32 v135, v246, v135, vcc
	v_cmp_le_u32_e32 vcc, v187, v201
	v_add_u32_e32 v187, 43, v0
	s_nop 0
	v_cndmask_b32_e32 v136, v246, v136, vcc
	v_cmp_le_u32_e32 vcc, v187, v201
	v_add_u32_e32 v187, 48, v0
	s_nop 0
	v_cndmask_b32_e32 v137, v246, v137, vcc
	v_cmp_le_u32_e32 vcc, v187, v201
	v_add_u32_e32 v187, 49, v0
	s_nop 0
	v_cndmask_b32_e32 v138, v246, v138, vcc
	v_cmp_le_u32_e32 vcc, v187, v201
	v_add_u32_e32 v187, 50, v0
	s_nop 0
	v_cndmask_b32_e32 v139, v246, v139, vcc
	v_cmp_le_u32_e32 vcc, v187, v201
	v_add_u32_e32 v187, 51, v0
	s_nop 0
	v_cndmask_b32_e32 v140, v246, v140, vcc
	v_cmp_le_u32_e32 vcc, v187, v201
	v_add_u32_e32 v187, 56, v0
	s_nop 0
	v_cndmask_b32_e32 v141, v246, v141, vcc
	v_cmp_le_u32_e32 vcc, v187, v201
	v_add_u32_e32 v187, 57, v0
	s_nop 0
	v_cndmask_b32_e32 v142, v246, v142, vcc
	v_cmp_le_u32_e32 vcc, v187, v201
	v_add_u32_e32 v187, 58, v0
	v_add_u32_e32 v0, 59, v0
	v_cndmask_b32_e32 v143, v246, v143, vcc
	v_cmp_le_u32_e32 vcc, v187, v201
	s_nop 1
	v_cndmask_b32_e32 v144, v246, v144, vcc
	v_cmp_le_u32_e32 vcc, v0, v201
	s_nop 1
	v_cndmask_b32_e32 v145, v246, v145, vcc
	s_branch .LBB0_1617
